# grid barrier waiters keep four staggered polls in flight instead of one
# baseline (speedup 1.0000x reference)
.Lmybar:
	v_readlane_b32 s100, v240, 35
	v_readlane_b32 s101, v240, 36
	v_mov_b32_e32 v247, 0x23fc0
	ds_read2_b32 v[248:249], v247 offset1:1
	v_mov_b32_e32 v250, s56
	v_lshlrev_b32_e32 v250, 8, v250
	v_add_u32_e32 v250, 0x1400, v250
	v_mov_b32_e32 v251, 1
	s_add_u32 s98, s98, 1
	s_waitcnt vmcnt(0)
	s_nop 1
	global_atomic_add v252, v250, v251, s[100:101] sc0
	s_waitcnt vmcnt(0) lgkmcnt(0)
	v_mul_lo_u32 v253, v248, s98
	v_add_u32_e32 v252, 1, v252
	v_add_u32_e32 v254, 0x1000, v250
	v_cmp_eq_u32_e32 vcc, v252, v253
	s_mov_b32 s96, 0
	s_cbranch_vccz .Lmb_local
	buffer_wbl2 sc1
	s_waitcnt vmcnt(0)
	v_mov_b32_e32 v250, 0x3400
	global_atomic_add v250, v251, s[100:101]
	buffer_inv sc1
	v_mul_lo_u32 v253, v249, s98
	s_mov_b32 s96, 1
	s_branch .Lmb_poll
.Lmb_local:
	buffer_inv sc1
	v_mov_b32_e32 v250, v254
	v_mov_b32_e32 v253, s98
.Lmb_poll:
	v_mov_b32_e32 v255, 0
	global_load_dword v252, v250, s[100:101] sc1
	s_sleep 8
	global_load_dword v247, v250, s[100:101] sc1
	s_sleep 8
	global_load_dword v248, v250, s[100:101] sc1
	s_sleep 8
	global_load_dword v249, v250, s[100:101] sc1
.Lmb_spin:
	s_waitcnt vmcnt(3)
	v_cmp_lt_u32_e32 vcc, v252, v253
	s_cbranch_vccz .Lmb_ok
	global_load_dword v252, v250, s[100:101] sc1
	s_waitcnt vmcnt(3)
	v_cmp_lt_u32_e32 vcc, v247, v253
	s_cbranch_vccz .Lmb_ok
	global_load_dword v247, v250, s[100:101] sc1
	s_waitcnt vmcnt(3)
	v_cmp_lt_u32_e32 vcc, v248, v253
	s_cbranch_vccz .Lmb_ok
	global_load_dword v248, v250, s[100:101] sc1
	s_waitcnt vmcnt(3)
	v_cmp_lt_u32_e32 vcc, v249, v253
	s_cbranch_vccz .Lmb_ok
	global_load_dword v249, v250, s[100:101] sc1
	v_add_u32_e32 v255, 1, v255
	v_cmp_gt_u32_e32 vcc, 0x10000, v255
	s_cbranch_vccnz .Lmb_spin
.Lmb_ok:
	s_cmp_eq_u32 s96, 1
	s_cbranch_scc0 .Lmb_done
	global_atomic_add v254, v251, s[100:101]
